# v18 + in the two fused up-proj phases the workgroups with one tile fewer (bid>=139) start ~4.5us late: epilogues of the two groups no longer coincide (power smoothing, no critical-path delay)
# baseline (speedup 1.0000x reference)
; #define PH_PRO(x) do {} while (0)
; #define PH_GS(x) do {} while (0)
; #define PH_GT(x) do {} while (0)
; __global__ void __launch_bounds__(512, 2) fwd_megakernel(Args a) {
;     ...
;         if (kind == K_NONE) continue;
;         for (int rep = 0; rep <= ((DUP_MASK >> step) & 1); ++rep) {
;         if (rep) __syncthreads();
;         if (kind == K_PRO) { PH_PRO(prologue(a, lds, G, bid)); }
;         else if (kind == K_GSCALE) { pg8::StaticOrder S; S.init(gm.M, gm.N, G, bid); pg8::EpiScale E{obf, ldo, ss, bias, mode};
;             PH_GS((pg8::gemm_phase<pg8::EpiScale, pg8::StaticOrder, true, true>(lds, gm, S, E)));
;             if (cset) { const int rem = S.nwg % G;
;                 if (rem == 0 || bid >= rem) { int t_ = threadIdx.x; asm volatile("" : "+v"(t_)); const int nw = (rem == 0) ? G : G - rem;
;                     convert_set(a, lds, cset, __builtin_amdgcn_readfirstlane(t_ >> 6), t_ & 63, ((rem == 0) ? bid : bid - rem) * 8 + (t_ >> 6), nw * 8); } } }
;         else if (kind == K_GSCALET) { pg8::StaticOrder S; S.init(gm.M, gm.N, G, bid); pg8::EpiScaleT E{obf, ldo, ss};
;             PH_GT((pg8::gemm_phase<pg8::EpiScaleT, pg8::StaticOrder, true, true>(lds, gm, S, E))); }
;         else if (kind == K_GCONV) { pg8::StaticOrder S; S.init(gm.M, gm.N, G, bid); pg8::EpiConv E{(bf16*)(ws + WS_HM), ss, a.in[10] + (size_t)layer * 3 * FF2, a.in[11] + (size_t)layer * FF2};
;             pg8::gemm_phase<pg8::EpiConv, pg8::StaticOrder, true, true>(lds, gm, S, E);
.LBB0_8:
	s_lshl_b32 s98, 1, s36
	s_and_b32 s98, s98, 0x1040
	s_cbranch_scc0 .Lmy_nostag
	v_readlane_b32 s98, v250, 0
	s_nop 3
	s_cmpk_lt_u32 s98, 139
	s_cbranch_scc1 .Lmy_nostag
	s_sleep 127
	s_sleep 40
